# prompt attention: q rows requested together with the k/v rows of the item (one exposed round trip per item instead of two)
# baseline (speedup 1.0000x reference)
; #define LAS __attribute__((address_space(3)))
; __device__ __forceinline__ void attn_prompt_item(LAS unsigned char* lds, const bf16_t* qkvb, bf16_t* og, float* lse, int it, int tid, int wave, int lane) {
;     ...
; #pragma unroll
;     for (int pp = 0; pp < 4; ++pp) {
;         const int p = tid + pp * NTHREADS, j = p >> 3, pc = p & 7, si = qb * 128 - 128 + j;
;         u32x4 kv = (u32x4){0u, 0u, 0u, 0u}, vv = (u32x4){0u, 0u, 0u, 0u};
;         if (si >= 0) { const bf16_t* kp = qkvb + (size_t)(b * SEQ + si * dil + r) * NQKV + colk + pc * 8; kv = *(const u32x4*)kp; vv = *(const u32x4*)(kp + AW); }
;         *(LAS u32x4*)(Kl + j * KL_PITCH + pc * 8) = kv;
;         LAS bf16_t* vd = Vt + (pc * 8) * VT_PITCH + ((((j >> 3) ^ pc) << 3) | (j & 7));
;         vd[0 * VT_PITCH] = (bf16_t)(vv.x & 0xffffu); vd[1 * VT_PITCH] = (bf16_t)(vv.x >> 16); vd[2 * VT_PITCH] = (bf16_t)(vv.y & 0xffffu); vd[3 * VT_PITCH] = (bf16_t)(vv.y >> 16);
;         vd[4 * VT_PITCH] = (bf16_t)(vv.z & 0xffffu); vd[5 * VT_PITCH] = (bf16_t)(vv.z >> 16); vd[6 * VT_PITCH] = (bf16_t)(vv.w & 0xffffu); vd[7 * VT_PITCH] = (bf16_t)(vv.w >> 16);
;     }
;     { const int d = tid >> 3, blk = 32 + (tid & 7); *(LAS u32x4*)(Vt + d * VT_PITCH + blk * 8) = (u32x4){0u, 0u, 0u, 0u}; }
;     const int ql = lane & 15, fq = lane >> 4;
;     const size_t qrow = (size_t)b * SEQ + (size_t)(qb * 128 + 16 * wave + ql) * dil + r;
;     const bf16_t* qp = qkvb + qrow * NQKV + g * 256 + hh * 64;
;     const bf16x8 q0 = *(const bf16x8*)(qp + 8 * fq), q1 = *(const bf16x8*)(qp + 32 + 8 * fq);
.Lattp_ld23:
	v_add_u32_e32 v196, s33, v26
	v_lshlrev_b32_e32 v196, s4, v196
	v_add_u32_e32 v196, s36, v196
	v_mad_i64_i32 v[196:197], s[6:7], v196, s42, v[8:9]
	global_load_dwordx4 v[222:225], v[196:197], off offset:1536
	global_load_dwordx4 v[226:229], v[196:197], off offset:3072
	v_add_u32_e32 v198, s33, v28
	v_lshlrev_b32_e32 v198, s4, v198
	v_add_u32_e32 v198, s36, v198
	v_mad_i64_i32 v[198:199], s[6:7], v198, s42, v[8:9]
	global_load_dwordx4 v[230:233], v[198:199], off offset:1536
	global_load_dwordx4 v[234:237], v[198:199], off offset:3072
	s_add_i32 s98, s31, s69
	v_or_b32_e32 v252, s98, v161
	v_mov_b32_e32 v253, 0
	v_lshlrev_b64 v[252:253], s4, v[252:253]
	s_sext_i32_i16 s98, s30
	s_ashr_i32 s99, s98, 31
	s_lshl_b64 s[98:99], s[98:99], 13
	s_or_b32 s98, s98, s28
	v_lshl_add_u64 v[254:255], s[98:99], 0, v[252:253]
	v_mov_b64_e32 v[252:253], s[24:25]
	v_mad_u64_u32 v[252:253], s[100:101], v254, s42, v[252:253]
	v_mov_b32_e32 v246, v253
	v_mad_u64_u32 v[246:247], s[100:101], v255, s42, v[246:247]
	v_mov_b32_e32 v253, v246
	s_lshl_b64 s[98:99], s[80:81], 1
	v_lshl_add_u64 v[252:253], v[252:253], 0, s[98:99]
	s_lshl_b32 s98, s26, 1
	s_mov_b32 s99, 0
	v_lshl_add_u64 v[252:253], v[252:253], 0, s[98:99]
	v_lshlrev_b32_e32 v254, 1, v154
	v_mov_b32_e32 v255, 0
	v_lshl_add_u64 v[252:253], v[252:253], 0, v[254:255]
	global_load_dwordx4 v[244:247], v[252:253], off
	global_load_dwordx4 v[248:251], v[252:253], off offset:64
	s_waitcnt vmcnt(9)
	ds_write_b128 v98, v[206:209]
	s_waitcnt vmcnt(8)
	ds_write_b16 v23, v210 offset:36864
	ds_write_b16_d16_hi v23, v210 offset:37520
	ds_write_b16 v23, v211 offset:38176
	ds_write_b16_d16_hi v23, v211 offset:38832
	ds_write_b16 v23, v212 offset:39488
	ds_write_b16_d16_hi v23, v212 offset:40144
	ds_write_b16 v23, v213 offset:40800
	ds_write_b16_d16_hi v23, v213 offset:41456
	s_lshl_b32 s78, s37, 2
	s_waitcnt vmcnt(7)
	ds_write_b128 v99, v[214:217]
	s_waitcnt vmcnt(6)
	ds_write_b16 v25, v218 offset:36864
	ds_write_b16_d16_hi v25, v218 offset:37520
	ds_write_b16 v25, v219 offset:38176
	ds_write_b16_d16_hi v25, v219 offset:38832
	ds_write_b16 v25, v220 offset:39488
	ds_write_b16_d16_hi v25, v220 offset:40144
	ds_write_b16 v25, v221 offset:40800
	ds_write_b16_d16_hi v25, v221 offset:41456
	s_or_b32 s6, s77, s78
	s_add_i32 s6, s6, 1
	v_cvt_f32_i32_e32 v10, s6
	v_mul_f32_e32 v10, 0xc1000000, v10
	v_div_scale_f32 v11, s[6:7], s43, s43, v10
	v_rcp_f32_e32 v12, v11
	s_waitcnt vmcnt(5)
	ds_write_b128 v100, v[222:225]
	v_fma_f32 v17, -v11, v12, 1.0
	v_fmac_f32_e32 v12, v17, v12
	v_div_scale_f32 v17, vcc, v10, s43, v10
	v_mul_f32_e32 v18, v17, v12
	v_fma_f32 v19, -v11, v18, v17
	v_fmac_f32_e32 v18, v19, v12
	v_fma_f32 v11, -v11, v18, v17
	v_div_fmas_f32 v11, v11, v12, v18
	v_div_fixup_f32 v10, v11, s43, v10
	s_waitcnt vmcnt(4)
	ds_write_b16 v27, v226 offset:36864
	ds_write_b16_d16_hi v27, v226 offset:37520
	ds_write_b16 v27, v227 offset:38176
	ds_write_b16_d16_hi v27, v227 offset:38832
	ds_write_b16 v27, v228 offset:39488
	ds_write_b16_d16_hi v27, v228 offset:40144
	ds_write_b16 v27, v229 offset:40800
	ds_write_b16_d16_hi v27, v229 offset:41456
	s_mov_b32 s6, 0xc2fc0000
	v_cmp_gt_f32_e32 vcc, s6, v10
	s_and_b64 s[6:7], vcc, exec
	s_cselect_b32 s6, 0xffffffc0, 0
	s_add_i32 s31, s31, s69
	v_or_b32_e32 v12, s31, v161
	s_lshl_b64 s[80:81], s[80:81], 1
	s_waitcnt vmcnt(3)
	ds_write_b128 v101, v[230:233]
	s_waitcnt vmcnt(2)
	ds_write_b16 v29, v234 offset:36864
	ds_write_b16_d16_hi v29, v234 offset:37520
	ds_write_b16 v29, v235 offset:38176
	ds_write_b16_d16_hi v29, v235 offset:38832
	ds_write_b16 v29, v236 offset:39488
	ds_write_b16_d16_hi v29, v236 offset:40144
	ds_write_b16 v29, v237 offset:40800
	ds_write_b16_d16_hi v29, v237 offset:41456
	v_cndmask_b32_e32 v0, 0, v133, vcc
	v_add_f32_e32 v0, v10, v0
	v_exp_f32_e32 v0, v0
	ds_write_b128 v30, v[174:177] offset:37376
	v_ldexp_f32 v21, v0, s6
	s_sext_i32_i16 s6, s30
	s_ashr_i32 s7, s6, 31
	s_lshl_b64 s[6:7], s[6:7], 13
	v_lshlrev_b64 v[0:1], s4, v[12:13]
	s_or_b32 s6, s6, s28
	v_lshl_add_u64 v[18:19], s[6:7], 0, v[0:1]
	v_mov_b64_e32 v[0:1], s[24:25]
	v_mad_u64_u32 v[0:1], s[6:7], v18, s42, v[0:1]
	v_mov_b32_e32 v2, v1
	v_mad_u64_u32 v[2:3], s[6:7], v19, s42, v[2:3]
	v_mov_b32_e32 v1, v2
	v_lshl_add_u64 v[0:1], v[0:1], 0, s[80:81]
	s_lshl_b32 s28, s26, 1
	v_lshl_add_u64 v[0:1], v[0:1], 0, s[28:29]
	v_lshlrev_b32_e32 v12, 1, v154
	v_lshl_add_u64 v[4:5], v[0:1], 0, v[12:13]
	s_waitcnt vmcnt(0)
	v_mov_b32_e32 v0, v244
	v_mov_b32_e32 v1, v245
	v_mov_b32_e32 v2, v246
	v_mov_b32_e32 v3, v247
	v_mov_b32_e32 v4, v248
	v_mov_b32_e32 v5, v249
	v_mov_b32_e32 v6, v250
	v_mov_b32_e32 v7, v251
	s_waitcnt lgkmcnt(0)
	s_barrier
; #define LAS __attribute__((address_space(3)))
; __device__ __forceinline__ void attn_prompt_item(LAS unsigned char* lds, const bf16_t* qkvb, bf16_t* og, float* lse, int it, int tid, int wave, int lane) {
;     ...
;     f32x4 sc[9]; float mx = -1e30f;
; #pragma unroll
;     for (int T = 0; T < 9; ++T) {
;         const LAS bf16_t* kr = Kl + (16 * (wave + T) + ql) * KL_PITCH + 8 * fq;
;         const bf16x8 a0 = *(const LAS bf16x8*)kr, a1 = *(const LAS bf16x8*)(kr + 32);
;         f32x4 acc = (f32x4){0.f, 0.f, 0.f, 0.f};
;         acc = __builtin_amdgcn_mfma_f32_16x16x32_bf16(a0, q0, acc, 0, 0, 0);
;         acc = __builtin_amdgcn_mfma_f32_16x16x32_bf16(a1, q1, acc, 0, 0, 0);
; #pragma unroll
;         for (int j = 0; j < 4; ++j) {
;             const int krel = 16 * T + 4 * fq + j, delta = 128 + ql - krel, ksub = qb * 128 - 128 + 16 * wave + krel;
;             const bool valid = (delta >= 0) && (delta <= 128) && (ksub >= 0);
;             const float s = valid ? acc[j] * 0.125f - slope * (float)(delta * dil) : -1e30f;
;             acc[j] = s; mx = fmaxf(mx, s); }
;         sc[T] = acc;
;     }
	ds_read_b128 v[8:11], v102
	ds_read_b128 v[136:139], v102 offset:64
	v_lshlrev_b32_e32 v12, s4, v31
	v_cvt_f32_u32_e32 v17, v12
	s_sub_i32 s26, 0x7f, s31
	v_cmp_lt_i32_e32 vcc, s26, v150
	s_and_b64 vcc, s[46:47], vcc
	s_mov_b32 s6, 0xf149f2ca
	s_waitcnt vmcnt(1) lgkmcnt(1)
	v_mfma_f32_16x16x32_bf16 v[8:11], v[8:11], v[0:3], 0
	s_waitcnt vmcnt(0) lgkmcnt(0)
	v_mfma_f32_16x16x32_bf16 v[8:11], v[136:139], v[4:7], v[8:11]
	s_nop 7
	v_mov_b32_e32 v20, v8
	v_pk_mul_f32 v[136:137], v[20:21], v[16:17]
	v_mov_b32_e32 v20, v9
	v_sub_f32_e32 v8, v136, v137
	v_cndmask_b32_e32 v12, v134, v8, vcc
	v_lshlrev_b32_e32 v8, s4, v32
	v_cvt_f32_u32_e32 v17, v8
	v_cmp_le_i32_e32 vcc, s26, v150
	s_and_b64 vcc, s[48:49], vcc
	v_pk_mul_f32 v[8:9], v[20:21], v[16:17]
	s_nop 0
	v_sub_f32_e32 v8, v8, v9
	v_cndmask_b32_e32 v136, v134, v8, vcc
	v_lshlrev_b32_e32 v8, s4, v33
	v_cvt_f32_u32_e32 v17, v8
	v_mov_b32_e32 v20, v10
	v_cmp_lt_i32_e32 vcc, s26, v151
	s_and_b64 vcc, s[50:51], vcc
	v_pk_mul_f32 v[8:9], v[20:21], v[16:17]
	v_mov_b32_e32 v20, v11
	v_sub_f32_e32 v8, v8, v9
	v_cndmask_b32_e32 v137, v134, v8, vcc
	v_lshlrev_b32_e32 v8, s4, v34
	v_cvt_f32_u32_e32 v17, v8
	v_cmp_lt_i32_e32 vcc, s26, v152
	s_and_b64 vcc, s[52:53], vcc
	v_max3_f32 v139, v12, s6, v136
	v_pk_mul_f32 v[8:9], v[20:21], v[16:17]
	v_lshlrev_b32_e32 v17, s4, v36
	v_sub_f32_e32 v8, v8, v9
	v_cndmask_b32_e32 v138, v134, v8, vcc
	ds_read_b128 v[8:11], v103
	ds_read_b128 v[140:143], v103 offset:64
	s_waitcnt lgkmcnt(1)
	v_mfma_f32_16x16x32_bf16 v[8:11], v[8:11], v[0:3], 0
	v_cvt_f32_u32_e32 v17, v17
	v_cmp_lt_i32_e32 vcc, s26, v35
	v_max3_f32 v139, v139, v137, v138
	s_waitcnt lgkmcnt(0)
	v_mfma_f32_16x16x32_bf16 v[8:11], v[140:143], v[4:7], v[8:11]
	s_nop 7
	v_mov_b32_e32 v20, v8
	v_pk_mul_f32 v[140:141], v[20:21], v[16:17]
	v_lshlrev_b32_e32 v17, s4, v38
	v_cvt_f32_u32_e32 v17, v17
	v_mov_b32_e32 v20, v9
	v_sub_f32_e32 v8, v140, v141
	v_cndmask_b32_e32 v8, v134, v8, vcc
	v_pk_mul_f32 v[140:141], v[20:21], v[16:17]
	v_lshlrev_b32_e32 v17, s4, v40
	v_cvt_f32_u32_e32 v17, v17
	v_mov_b32_e32 v20, v10
	v_cmp_lt_i32_e32 vcc, s26, v37
	v_sub_f32_e32 v9, v140, v141
	v_pk_mul_f32 v[140:141], v[20:21], v[16:17]
	v_cndmask_b32_e32 v9, v134, v9, vcc
	v_cmp_lt_i32_e32 vcc, s26, v39
	v_sub_f32_e32 v10, v140, v141
	v_max3_f32 v142, v139, v8, v9
	v_cndmask_b32_e32 v139, v134, v10, vcc
	v_lshlrev_b32_e32 v10, s4, v42
	v_cvt_f32_u32_e32 v17, v10
	v_mov_b32_e32 v20, v11
	v_cmp_lt_i32_e32 vcc, s26, v41
	v_pk_mul_f32 v[10:11], v[20:21], v[16:17]
	s_nop 0
	v_sub_f32_e32 v10, v10, v11
	v_cndmask_b32_e32 v10, v134, v10, vcc
	v_max3_f32 v148, v142, v139, v10
	ds_read_b128 v[140:143], v104
	ds_read_b128 v[144:147], v104 offset:64
	s_waitcnt lgkmcnt(1)
	v_mfma_f32_16x16x32_bf16 v[140:143], v[140:143], v[0:3], 0
	v_lshlrev_b32_e32 v11, s4, v44
	v_cvt_f32_u32_e32 v17, v11
	v_cmp_lt_i32_e32 vcc, s26, v43
	s_waitcnt lgkmcnt(0)
	v_mfma_f32_16x16x32_bf16 v[140:143], v[144:147], v[4:7], v[140:143]
	s_nop 7
	v_mov_b32_e32 v20, v140
	v_pk_mul_f32 v[144:145], v[20:21], v[16:17]
	v_lshlrev_b32_e32 v17, s4, v46
	v_cvt_f32_u32_e32 v17, v17
	v_mov_b32_e32 v20, v141
	v_sub_f32_e32 v11, v144, v145
	v_cndmask_b32_e32 v11, v134, v11, vcc
	v_pk_mul_f32 v[140:141], v[20:21], v[16:17]
	v_cmp_lt_i32_e32 vcc, s26, v45
	v_sub_f32_e32 v17, v140, v141
	v_mov_b32_e32 v20, v142
	v_cndmask_b32_e32 v140, v134, v17, vcc
	v_lshlrev_b32_e32 v17, s4, v48
	v_cvt_f32_u32_e32 v17, v17
	v_cmp_lt_i32_e32 vcc, s26, v47
	v_max3_f32 v146, v148, v11, v140
	v_pk_mul_f32 v[144:145], v[20:21], v[16:17]
	s_nop 0
	v_sub_f32_e32 v17, v144, v145
	v_cndmask_b32_e32 v142, v134, v17, vcc
	v_lshlrev_b32_e32 v17, s4, v50
	v_cvt_f32_u32_e32 v17, v17
	v_mov_b32_e32 v20, v143
	v_cmp_lt_i32_e32 vcc, s26, v49
	v_pk_mul_f32 v[144:145], v[20:21], v[16:17]
	s_nop 0
	v_sub_f32_e32 v17, v144, v145
	v_cndmask_b32_e32 v141, v134, v17, vcc
	v_max3_f32 v155, v146, v142, v141
	ds_read_b128 v[144:147], v105
	ds_read_b128 v[156:159], v105 offset:64
	s_waitcnt lgkmcnt(1)
	v_mfma_f32_16x16x32_bf16 v[144:147], v[144:147], v[0:3], 0
	v_lshlrev_b32_e32 v17, s4, v52
	v_cvt_f32_u32_e32 v17, v17
	v_cmp_lt_i32_e32 vcc, s26, v51
	s_waitcnt lgkmcnt(0)
	v_mfma_f32_16x16x32_bf16 v[144:147], v[156:159], v[4:7], v[144:147]
	ds_read_b128 v[156:159], v106
	ds_read_b128 v[166:169], v106 offset:64
	s_waitcnt lgkmcnt(1)
	v_mfma_f32_16x16x32_bf16 v[156:159], v[156:159], v[0:3], 0
	s_nop 3
	v_mov_b32_e32 v20, v144
	v_pk_mul_f32 v[148:149], v[20:21], v[16:17]
	v_mov_b32_e32 v20, v145
	v_sub_f32_e32 v17, v148, v149
	v_cndmask_b32_e32 v143, v134, v17, vcc
	v_lshlrev_b32_e32 v17, s4, v54
	v_cvt_f32_u32_e32 v17, v17
	v_cmp_lt_i32_e32 vcc, s26, v53
	s_waitcnt lgkmcnt(0)
	v_mfma_f32_16x16x32_bf16 v[156:159], v[166:169], v[4:7], v[156:159]
	v_mul_f32_e64 v144, v20, v16
	v_mul_f32_e64 v145, v21, v17
	v_sub_f32_e32 v17, v144, v145
	v_cndmask_b32_e32 v144, v134, v17, vcc
	v_lshlrev_b32_e32 v17, s4, v56
	v_cvt_f32_u32_e32 v17, v17
	v_mov_b32_e32 v20, v146
	v_cmp_lt_i32_e32 vcc, s26, v55
	v_max3_f32 v155, v155, v143, v144
	v_pk_mul_f32 v[148:149], v[20:21], v[16:17]
	v_mov_b32_e32 v20, v147
	v_sub_f32_e32 v17, v148, v149
	v_cndmask_b32_e32 v146, v134, v17, vcc
	v_lshlrev_b32_e32 v17, s4, v58
	v_cvt_f32_u32_e32 v17, v17
	v_cmp_lt_i32_e32 vcc, s26, v57
	v_pk_mul_f32 v[148:149], v[20:21], v[16:17]
	s_nop 0
	v_sub_f32_e32 v17, v148, v149
	v_cndmask_b32_e32 v145, v134, v17, vcc
	v_lshlrev_b32_e32 v17, s4, v60
	v_cvt_f32_u32_e32 v17, v17
	v_mov_b32_e32 v20, v156
	v_cmp_lt_i32_e32 vcc, s26, v59
	v_max3_f32 v155, v155, v146, v145
	v_pk_mul_f32 v[148:149], v[20:21], v[16:17]
	v_mov_b32_e32 v20, v157
	v_sub_f32_e32 v17, v148, v149
	v_cndmask_b32_e32 v147, v134, v17, vcc
	v_lshlrev_b32_e32 v17, s4, v62
	v_cvt_f32_u32_e32 v17, v17
	v_cmp_lt_i32_e32 vcc, s26, v61
	v_pk_mul_f32 v[148:149], v[20:21], v[16:17]
	s_nop 0
	v_sub_f32_e32 v17, v148, v149
	v_cndmask_b32_e32 v148, v134, v17, vcc
	v_lshlrev_b32_e32 v17, s4, v64
	v_cvt_f32_u32_e32 v17, v17
	v_mov_b32_e32 v20, v158
	v_cmp_lt_i32_e32 vcc, s26, v63
	v_max3_f32 v163, v155, v147, v148
	v_pk_mul_f32 v[156:157], v[20:21], v[16:17]
	v_mov_b32_e32 v20, v159
	v_sub_f32_e32 v17, v156, v157
	v_cndmask_b32_e32 v155, v134, v17, vcc
	v_lshlrev_b32_e32 v17, s4, v66
	v_cvt_f32_u32_e32 v17, v17
	v_cmp_lt_i32_e32 vcc, s26, v65
	v_pk_mul_f32 v[156:157], v[20:21], v[16:17]
	s_nop 0
	v_sub_f32_e32 v17, v156, v157
	ds_read_b128 v[156:159], v107
	ds_read_b128 v[166:169], v107 offset:64
	s_waitcnt lgkmcnt(1)
; #define LAS __attribute__((address_space(3)))
; __device__ __forceinline__ void attn_prompt_item(LAS unsigned char* lds, const bf16_t* qkvb, bf16_t* og, float* lse, int it, int tid, int wave, int lane) {
;     ...
;     for (int T = 0; T < 9; ++T) {
;         const LAS bf16_t* kr = Kl + (16 * (wave + T) + ql) * KL_PITCH + 8 * fq;
;         const bf16x8 a0 = *(const LAS bf16x8*)kr, a1 = *(const LAS bf16x8*)(kr + 32);
;         f32x4 acc = (f32x4){0.f, 0.f, 0.f, 0.f};
;         acc = __builtin_amdgcn_mfma_f32_16x16x32_bf16(a0, q0, acc, 0, 0, 0);
;         acc = __builtin_amdgcn_mfma_f32_16x16x32_bf16(a1, q1, acc, 0, 0, 0);
; #pragma unroll
;         for (int j = 0; j < 4; ++j) {
;             const int krel = 16 * T + 4 * fq + j, delta = 128 + ql - krel, ksub = qb * 128 - 128 + 16 * wave + krel;
;             const bool valid = (delta >= 0) && (delta <= 128) && (ksub >= 0);
;             const float s = valid ? acc[j] * 0.125f - slope * (float)(delta * dil) : -1e30f;
;             acc[j] = s; mx = fmaxf(mx, s); }
;         sc[T] = acc;
;     }
;     mx = fmaxf(mx, __shfl_xor(mx, 16)); mx = fmaxf(mx, __shfl_xor(mx, 32));
	v_mfma_f32_16x16x32_bf16 v[156:159], v[156:159], v[0:3], 0
	v_cndmask_b32_e32 v149, v134, v17, vcc
	v_lshlrev_b32_e32 v17, s4, v68
	v_cvt_f32_u32_e32 v17, v17
	s_waitcnt lgkmcnt(0)
	v_mfma_f32_16x16x32_bf16 v[166:169], v[166:169], v[4:7], v[156:159]
	v_cmp_lt_i32_e32 vcc, s26, v67
	v_max3_f32 v163, v163, v155, v149
	s_nop 5
	v_mov_b32_e32 v20, v166
	v_pk_mul_f32 v[156:157], v[20:21], v[16:17]
	v_mov_b32_e32 v20, v167
	v_sub_f32_e32 v17, v156, v157
	v_cndmask_b32_e32 v156, v134, v17, vcc
	v_lshlrev_b32_e32 v17, s4, v70
	v_cvt_f32_u32_e32 v17, v17
	v_cmp_lt_i32_e32 vcc, s26, v69
	v_pk_mul_f32 v[158:159], v[20:21], v[16:17]
	s_nop 0
	v_sub_f32_e32 v17, v158, v159
	v_cndmask_b32_e32 v157, v134, v17, vcc
	v_lshlrev_b32_e32 v17, s4, v72
	v_cvt_f32_u32_e32 v17, v17
	v_mov_b32_e32 v20, v168
	v_cmp_lt_i32_e32 vcc, s26, v71
	v_max3_f32 v163, v163, v156, v157
	v_pk_mul_f32 v[158:159], v[20:21], v[16:17]
	v_mov_b32_e32 v20, v169
	v_sub_f32_e32 v17, v158, v159
	v_cndmask_b32_e32 v159, v134, v17, vcc
	v_lshlrev_b32_e32 v17, s4, v74
	v_cvt_f32_u32_e32 v17, v17
	v_cmp_lt_i32_e32 vcc, s26, v73
	v_pk_mul_f32 v[166:167], v[20:21], v[16:17]
	s_nop 0
	v_sub_f32_e32 v17, v166, v167
	ds_read_b128 v[166:169], v108
	ds_read_b128 v[178:181], v108 offset:64
	s_waitcnt lgkmcnt(1)
	v_mfma_f32_16x16x32_bf16 v[166:169], v[166:169], v[0:3], 0
	v_cndmask_b32_e32 v158, v134, v17, vcc
	v_lshlrev_b32_e32 v17, s4, v76
	v_cvt_f32_u32_e32 v17, v17
	s_waitcnt lgkmcnt(0)
	v_mfma_f32_16x16x32_bf16 v[166:169], v[178:181], v[4:7], v[166:169]
	v_cmp_lt_i32_e32 vcc, s26, v75
	v_max3_f32 v171, v163, v159, v158
	ds_read_b128 v[178:181], v109
	ds_read_b128 v[182:185], v109 offset:64
	s_waitcnt lgkmcnt(1)
	v_mfma_f32_16x16x32_bf16 v[178:181], v[178:181], v[0:3], 0
	s_nop 1
	v_mov_b32_e32 v20, v166
	v_pk_mul_f32 v[172:173], v[20:21], v[16:17]
	v_mov_b32_e32 v20, v167
	v_sub_f32_e32 v17, v172, v173
	v_cndmask_b32_e32 v163, v134, v17, vcc
	v_lshlrev_b32_e32 v17, s4, v78
	v_cvt_f32_u32_e32 v17, v17
	v_cmp_lt_i32_e32 vcc, s26, v77
	s_waitcnt lgkmcnt(0)
	v_mfma_f32_16x16x32_bf16 v[178:181], v[182:185], v[4:7], v[178:181]
	v_mul_f32_e64 v166, v20, v16
	v_mul_f32_e64 v167, v21, v17
	v_sub_f32_e32 v17, v166, v167
	v_cndmask_b32_e32 v166, v134, v17, vcc
	v_lshlrev_b32_e32 v17, s4, v80
	v_cvt_f32_u32_e32 v17, v17
	v_mov_b32_e32 v20, v168
	v_cmp_lt_i32_e32 vcc, s26, v79
	v_max3_f32 v171, v171, v163, v166
	v_pk_mul_f32 v[172:173], v[20:21], v[16:17]
	v_mov_b32_e32 v20, v169
	v_sub_f32_e32 v17, v172, v173
	v_cndmask_b32_e32 v168, v134, v17, vcc
	v_lshlrev_b32_e32 v17, s4, v82
	v_cvt_f32_u32_e32 v17, v17
	v_cmp_lt_i32_e32 vcc, s26, v81
	v_pk_mul_f32 v[172:173], v[20:21], v[16:17]
	s_nop 0
	v_sub_f32_e32 v17, v172, v173
	v_cndmask_b32_e32 v167, v134, v17, vcc
	v_lshlrev_b32_e32 v17, s4, v84
	v_cvt_f32_u32_e32 v17, v17
	v_mov_b32_e32 v20, v178
	v_cmp_lt_i32_e32 vcc, s26, v83
	v_max3_f32 v186, v171, v168, v167
	v_pk_mul_f32 v[172:173], v[20:21], v[16:17]
	v_mov_b32_e32 v20, v179
	v_sub_f32_e32 v17, v172, v173
	v_cndmask_b32_e32 v169, v134, v17, vcc
	v_lshlrev_b32_e32 v17, s4, v86
	v_cvt_f32_u32_e32 v17, v17
	v_cmp_lt_i32_e32 vcc, s26, v85
	v_pk_mul_f32 v[172:173], v[20:21], v[16:17]
	s_nop 0
	v_sub_f32_e32 v17, v172, v173
	v_cndmask_b32_e32 v171, v134, v17, vcc
	v_lshlrev_b32_e32 v17, s4, v88
	v_cvt_f32_u32_e32 v17, v17
	v_mov_b32_e32 v20, v180
	v_cmp_lt_i32_e32 vcc, s26, v87
	v_max3_f32 v182, v186, v169, v171
	v_pk_mul_f32 v[172:173], v[20:21], v[16:17]
	v_mov_b32_e32 v20, v181
	v_sub_f32_e32 v17, v172, v173
	v_cndmask_b32_e32 v173, v134, v17, vcc
	v_lshlrev_b32_e32 v17, s4, v90
	v_cvt_f32_u32_e32 v17, v17
	v_cmp_lt_i32_e32 vcc, s26, v89
	v_pk_mul_f32 v[178:179], v[20:21], v[16:17]
	s_nop 0
	v_sub_f32_e32 v17, v178, v179
	v_cndmask_b32_e32 v172, v134, v17, vcc
	v_max3_f32 v186, v182, v173, v172
	ds_read_b128 v[178:181], v110
	ds_read_b128 v[182:185], v110 offset:64
	s_waitcnt lgkmcnt(1)
	v_mfma_f32_16x16x32_bf16 v[0:3], v[178:181], v[0:3], 0
	v_cmp_lt_f32_e32 vcc, s67, v12
	s_waitcnt lgkmcnt(0)
	v_mfma_f32_16x16x32_bf16 v[2:5], v[182:185], v[4:7], v[0:3]
	s_nop 4
	v_lshlrev_b32_e32 v0, s4, v91
	v_cvt_f32_i32_e32 v17, v0
	s_nop 0
	v_mov_b32_e32 v20, v2
	v_pk_mul_f32 v[0:1], v[20:21], v[16:17]
	s_nop 0
	v_sub_f32_e32 v0, v0, v1
	v_lshlrev_b32_e32 v1, s4, v92
	v_cvt_f32_i32_e32 v17, v1
	v_mov_b32_e32 v20, v3
	v_cndmask_b32_e64 v0, v134, v0, s[54:55]
	v_pk_mul_f32 v[2:3], v[20:21], v[16:17]
	s_nop 0
	v_sub_f32_e32 v1, v2, v3
	v_lshlrev_b32_e32 v2, s4, v93
	v_cvt_f32_i32_e32 v17, v2
	v_mov_b32_e32 v20, v4
	v_cndmask_b32_e64 v1, v134, v1, s[56:57]
	v_max3_f32 v6, v186, v0, v1
	v_pk_mul_f32 v[2:3], v[20:21], v[16:17]
	v_mov_b32_e32 v20, v5
	v_sub_f32_e32 v2, v2, v3
	v_cndmask_b32_e64 v3, v134, v2, s[58:59]
	v_lshlrev_b32_e32 v2, s4, v94
	v_cvt_f32_i32_e32 v17, v2
	v_pk_mul_f32 v[4:5], v[20:21], v[16:17]
	s_nop 0
	v_sub_f32_e32 v2, v4, v5
	v_cndmask_b32_e64 v4, v134, v2, s[60:61]
	v_max3_f32 v2, v6, v3, v4
	ds_bpermute_b32 v5, v96, v2
	s_waitcnt lgkmcnt(0)
	v_max_f32_e32 v5, v5, v5
	v_max_f32_e32 v2, v2, v5
	ds_bpermute_b32 v5, v97, v2
	s_waitcnt lgkmcnt(0)
; __device__ __forceinline__ unsigned cvt_pk_bf16(float lo, float hi) { unsigned r; asm volatile("v_cvt_pk_bf16_f32 %0, %1, %2" : "=v"(r) : "v"(lo), "v"(hi)); return r; }
; #define LAS __attribute__((address_space(3)))
; __device__ __forceinline__ void attn_prompt_item(LAS unsigned char* lds, const bf16_t* qkvb, bf16_t* og, float* lse, int it, int tid, int wave, int lane) {
;     ...
;     float den = 0.f;
; #pragma unroll
;     for (int T = 0; T < 9; ++T) {
;         f32x4 p;
; #pragma unroll
;         for (int j = 0; j < 4; ++j) { p[j] = sc[T][j] > -1e29f ? __expf(sc[T][j] - mx) : 0.f; den += p[j]; }
;         u32x2 w; w.x = cvt_pk_bf16(p[0], p[1]); w.y = cvt_pk_bf16(p[2], p[3]);
;         *(LAS u32x2*)(Pw + ql * PW_PITCH + 16 * T + 4 * fq) = w;
;     }
	v_max_f32_e32 v5, v5, v5
	v_max_f32_e32 v2, v2, v5
	v_sub_f32_e32 v5, v12, v2
	v_mul_f32_e32 v5, 0x3fb8aa3b, v5
	v_sub_f32_e32 v7, v136, v2
	v_exp_f32_e32 v5, v5
	v_mul_f32_e32 v7, 0x3fb8aa3b, v7
	v_sub_f32_e32 v12, v137, v2
	v_exp_f32_e32 v7, v7
	v_mul_f32_e32 v12, 0x3fb8aa3b, v12
	v_sub_f32_e32 v17, v138, v2
	v_exp_f32_e32 v12, v12
	v_mul_f32_e32 v17, 0x3fb8aa3b, v17
	v_exp_f32_e32 v17, v17
	v_cndmask_b32_e32 v5, 0, v5, vcc
	v_cmp_lt_f32_e32 vcc, s67, v136
	v_add_f32_e32 v6, 0, v5
	s_nop 0
	v_cndmask_b32_e32 v7, 0, v7, vcc
	v_cmp_lt_f32_e32 vcc, s67, v137
	v_add_f32_e32 v6, v7, v6
	s_nop 0
	v_cndmask_b32_e32 v12, 0, v12, vcc
	v_cmp_lt_f32_e32 vcc, s67, v138
	v_add_f32_e32 v6, v12, v6
	s_nop 0
	v_cndmask_b32_e32 v17, 0, v17, vcc
	v_add_f32_e32 v20, v17, v6
	v_cvt_pk_bf16_f32 v6, v5, v7
	v_sub_f32_e32 v5, v8, v2
	v_mul_f32_e32 v5, 0x3fb8aa3b, v5
	v_exp_f32_e32 v5, v5
	v_cvt_pk_bf16_f32 v7, v12, v17
	ds_write_b64 v95, v[6:7]
	v_sub_f32_e32 v7, v9, v2
	v_cmp_lt_f32_e32 vcc, s67, v8
	v_mul_f32_e32 v7, 0x3fb8aa3b, v7
	v_sub_f32_e32 v8, v139, v2
	v_cndmask_b32_e32 v5, 0, v5, vcc
	v_cmp_lt_f32_e32 vcc, s67, v9
	v_exp_f32_e32 v7, v7
	v_mul_f32_e32 v8, 0x3fb8aa3b, v8
	v_sub_f32_e32 v9, v10, v2
	v_exp_f32_e32 v8, v8
	v_mul_f32_e32 v9, 0x3fb8aa3b, v9
	v_exp_f32_e32 v9, v9
	v_add_f32_e32 v6, v5, v20
	v_cndmask_b32_e32 v7, 0, v7, vcc
	v_cmp_lt_f32_e32 vcc, s67, v139
	v_add_f32_e32 v6, v7, v6
	v_mov_b32_e32 v12, v13
	v_cndmask_b32_e32 v8, 0, v8, vcc
	v_cmp_lt_f32_e32 vcc, s67, v10
	v_add_f32_e32 v6, v8, v6
	s_nop 0
	v_cndmask_b32_e32 v9, 0, v9, vcc
	v_add_f32_e32 v10, v9, v6
	v_cvt_pk_bf16_f32 v6, v5, v7
	v_cvt_pk_bf16_f32 v7, v8, v9
	v_sub_f32_e32 v5, v11, v2
	ds_write_b64 v95, v[6:7] offset:32
	v_mul_f32_e32 v5, 0x3fb8aa3b, v5
	v_sub_f32_e32 v7, v140, v2
	v_exp_f32_e32 v5, v5
	v_mul_f32_e32 v7, 0x3fb8aa3b, v7
	v_sub_f32_e32 v8, v142, v2
	v_exp_f32_e32 v7, v7
	v_mul_f32_e32 v8, 0x3fb8aa3b, v8
	v_sub_f32_e32 v9, v141, v2
	v_exp_f32_e32 v8, v8
	v_mul_f32_e32 v9, 0x3fb8aa3b, v9
	v_cmp_lt_f32_e32 vcc, s67, v11
	v_exp_f32_e32 v9, v9
	s_nop 0
	v_cndmask_b32_e32 v5, 0, v5, vcc
	v_cmp_lt_f32_e32 vcc, s67, v140
	v_add_f32_e32 v6, v5, v10
	s_nop 0
	v_cndmask_b32_e32 v7, 0, v7, vcc
	v_cmp_lt_f32_e32 vcc, s67, v142
	v_add_f32_e32 v6, v7, v6
	s_nop 0
	v_cndmask_b32_e32 v8, 0, v8, vcc
	v_cmp_lt_f32_e32 vcc, s67, v141
	v_add_f32_e32 v6, v8, v6
	s_nop 0
	v_cndmask_b32_e32 v9, 0, v9, vcc
	v_add_f32_e32 v10, v9, v6
	v_cvt_pk_bf16_f32 v6, v5, v7
	v_cvt_pk_bf16_f32 v7, v8, v9
	v_sub_f32_e32 v5, v143, v2
	ds_write_b64 v95, v[6:7] offset:64
	v_mul_f32_e32 v5, 0x3fb8aa3b, v5
	v_sub_f32_e32 v7, v144, v2
	v_exp_f32_e32 v5, v5
	v_mul_f32_e32 v7, 0x3fb8aa3b, v7
	v_sub_f32_e32 v8, v146, v2
	v_exp_f32_e32 v7, v7
	v_mul_f32_e32 v8, 0x3fb8aa3b, v8
	v_sub_f32_e32 v9, v145, v2
	v_exp_f32_e32 v8, v8
	v_mul_f32_e32 v9, 0x3fb8aa3b, v9
	v_cmp_lt_f32_e32 vcc, s67, v143
	v_exp_f32_e32 v9, v9
	s_nop 0
	v_cndmask_b32_e32 v5, 0, v5, vcc
	v_cmp_lt_f32_e32 vcc, s67, v144
	v_add_f32_e32 v6, v5, v10
	s_nop 0
	v_cndmask_b32_e32 v7, 0, v7, vcc
	v_cmp_lt_f32_e32 vcc, s67, v146
	v_add_f32_e32 v6, v7, v6
	s_nop 0
	v_cndmask_b32_e32 v8, 0, v8, vcc
	v_cmp_lt_f32_e32 vcc, s67, v145
	v_add_f32_e32 v6, v8, v6
	s_nop 0
	v_cndmask_b32_e32 v9, 0, v9, vcc
	v_add_f32_e32 v10, v9, v6
	v_cvt_pk_bf16_f32 v6, v5, v7
	v_cvt_pk_bf16_f32 v7, v8, v9
	v_sub_f32_e32 v5, v147, v2
	ds_write_b64 v95, v[6:7] offset:96
	v_mul_f32_e32 v5, 0x3fb8aa3b, v5
	v_sub_f32_e32 v7, v148, v2
	v_exp_f32_e32 v5, v5
	v_mul_f32_e32 v7, 0x3fb8aa3b, v7
	v_sub_f32_e32 v8, v155, v2
	v_exp_f32_e32 v7, v7
	v_mul_f32_e32 v8, 0x3fb8aa3b, v8
	v_sub_f32_e32 v9, v149, v2
	v_exp_f32_e32 v8, v8
	v_mul_f32_e32 v9, 0x3fb8aa3b, v9
	v_cmp_lt_f32_e32 vcc, s67, v147
	v_exp_f32_e32 v9, v9
	s_nop 0
	v_cndmask_b32_e32 v5, 0, v5, vcc
	v_cmp_lt_f32_e32 vcc, s67, v148
	v_add_f32_e32 v6, v5, v10
	s_nop 0
	v_cndmask_b32_e32 v7, 0, v7, vcc
	v_cmp_lt_f32_e32 vcc, s67, v155
	v_add_f32_e32 v6, v7, v6
	s_nop 0
	v_cndmask_b32_e32 v8, 0, v8, vcc
	v_cmp_lt_f32_e32 vcc, s67, v149
	v_add_f32_e32 v6, v8, v6
	s_nop 0
	v_cndmask_b32_e32 v9, 0, v9, vcc
	v_add_f32_e32 v10, v9, v6
	v_cvt_pk_bf16_f32 v6, v5, v7
	v_cvt_pk_bf16_f32 v7, v8, v9
	v_sub_f32_e32 v5, v156, v2
	ds_write_b64 v95, v[6:7] offset:128
	v_mul_f32_e32 v5, 0x3fb8aa3b, v5
	v_sub_f32_e32 v7, v157, v2
	v_exp_f32_e32 v5, v5
	v_mul_f32_e32 v7, 0x3fb8aa3b, v7
	v_sub_f32_e32 v8, v159, v2
	v_exp_f32_e32 v7, v7
	v_mul_f32_e32 v8, 0x3fb8aa3b, v8
	v_sub_f32_e32 v9, v158, v2
	v_exp_f32_e32 v8, v8
	v_mul_f32_e32 v9, 0x3fb8aa3b, v9
	v_cmp_lt_f32_e32 vcc, s67, v156
	v_exp_f32_e32 v9, v9
	s_nop 0
	v_cndmask_b32_e32 v5, 0, v5, vcc
	v_cmp_lt_f32_e32 vcc, s67, v157
	v_add_f32_e32 v6, v5, v10
	s_nop 0
	v_cndmask_b32_e32 v7, 0, v7, vcc
	v_cmp_lt_f32_e32 vcc, s67, v159
	v_add_f32_e32 v6, v7, v6
	s_nop 0
	v_cndmask_b32_e32 v8, 0, v8, vcc
	v_cmp_lt_f32_e32 vcc, s67, v158
	v_add_f32_e32 v6, v8, v6
	s_nop 0
	v_cndmask_b32_e32 v9, 0, v9, vcc
	v_add_f32_e32 v10, v9, v6
	v_cvt_pk_bf16_f32 v6, v5, v7
	v_cvt_pk_bf16_f32 v7, v8, v9
	v_sub_f32_e32 v5, v163, v2
	ds_write_b64 v95, v[6:7] offset:160
	v_mul_f32_e32 v5, 0x3fb8aa3b, v5
	v_sub_f32_e32 v7, v166, v2
	v_exp_f32_e32 v5, v5
	v_mul_f32_e32 v7, 0x3fb8aa3b, v7
	v_sub_f32_e32 v8, v168, v2
	v_exp_f32_e32 v7, v7
	v_mul_f32_e32 v8, 0x3fb8aa3b, v8
	v_sub_f32_e32 v9, v167, v2
	v_exp_f32_e32 v8, v8
	v_mul_f32_e32 v9, 0x3fb8aa3b, v9
	v_cmp_lt_f32_e32 vcc, s67, v163
	v_exp_f32_e32 v9, v9
	s_nop 0
	v_cndmask_b32_e32 v5, 0, v5, vcc
	v_cmp_lt_f32_e32 vcc, s67, v166
	v_add_f32_e32 v6, v5, v10
	s_nop 0
	v_cndmask_b32_e32 v7, 0, v7, vcc
	v_cmp_lt_f32_e32 vcc, s67, v168
	v_add_f32_e32 v6, v7, v6
	s_nop 0
; __device__ __forceinline__ unsigned cvt_pk_bf16(float lo, float hi) { unsigned r; asm volatile("v_cvt_pk_bf16_f32 %0, %1, %2" : "=v"(r) : "v"(lo), "v"(hi)); return r; }
; #define LAS __attribute__((address_space(3)))
; __device__ __forceinline__ void attn_prompt_item(LAS unsigned char* lds, const bf16_t* qkvb, bf16_t* og, float* lse, int it, int tid, int wave, int lane) {
;     ...
; #pragma unroll
;     for (int T = 0; T < 9; ++T) {
;         f32x4 p;
; #pragma unroll
;         for (int j = 0; j < 4; ++j) { p[j] = sc[T][j] > -1e29f ? __expf(sc[T][j] - mx) : 0.f; den += p[j]; }
;         u32x2 w; w.x = cvt_pk_bf16(p[0], p[1]); w.y = cvt_pk_bf16(p[2], p[3]);
;         *(LAS u32x2*)(Pw + ql * PW_PITCH + 16 * T + 4 * fq) = w;
;     }
;     *(LAS u32x2*)(Pw + ql * PW_PITCH + 144 + 4 * fq) = (u32x2){0u, 0u};
;     den += __shfl_xor(den, 16); den += __shfl_xor(den, 32);
;     const float inv = 1.0f / den;
;     __syncthreads();
	v_cndmask_b32_e32 v8, 0, v8, vcc
	v_cmp_lt_f32_e32 vcc, s67, v167
	v_add_f32_e32 v6, v8, v6
	s_nop 0
	v_cndmask_b32_e32 v9, 0, v9, vcc
	v_add_f32_e32 v10, v9, v6
	v_cvt_pk_bf16_f32 v6, v5, v7
	v_cvt_pk_bf16_f32 v7, v8, v9
	v_sub_f32_e32 v5, v169, v2
	ds_write_b64 v95, v[6:7] offset:192
	v_mul_f32_e32 v5, 0x3fb8aa3b, v5
	v_sub_f32_e32 v7, v171, v2
	v_exp_f32_e32 v5, v5
	v_mul_f32_e32 v7, 0x3fb8aa3b, v7
	v_sub_f32_e32 v8, v173, v2
	v_exp_f32_e32 v7, v7
	v_mul_f32_e32 v8, 0x3fb8aa3b, v8
	v_sub_f32_e32 v9, v172, v2
	v_exp_f32_e32 v8, v8
	v_mul_f32_e32 v9, 0x3fb8aa3b, v9
	v_cmp_lt_f32_e32 vcc, s67, v169
	v_exp_f32_e32 v9, v9
	s_nop 0
	v_cndmask_b32_e32 v5, 0, v5, vcc
	v_cmp_lt_f32_e32 vcc, s67, v171
	v_add_f32_e32 v6, v5, v10
	s_nop 0
	v_cndmask_b32_e32 v7, 0, v7, vcc
	v_cmp_lt_f32_e32 vcc, s67, v173
	v_add_f32_e32 v6, v7, v6
	s_nop 0
	v_cndmask_b32_e32 v8, 0, v8, vcc
	v_cmp_lt_f32_e32 vcc, s67, v172
	v_add_f32_e32 v6, v8, v6
	s_nop 0
	v_cndmask_b32_e32 v9, 0, v9, vcc
	v_cmp_lt_f32_e32 vcc, s67, v0
	v_sub_f32_e32 v0, v0, v2
	v_mul_f32_e32 v0, 0x3fb8aa3b, v0
	v_exp_f32_e32 v0, v0
	v_add_f32_e32 v10, v9, v6
	v_cvt_pk_bf16_f32 v6, v5, v7
	v_cvt_pk_bf16_f32 v7, v8, v9
	v_cndmask_b32_e32 v0, 0, v0, vcc
	v_cmp_lt_f32_e32 vcc, s67, v1
	v_sub_f32_e32 v1, v1, v2
	v_mul_f32_e32 v1, 0x3fb8aa3b, v1
	v_exp_f32_e32 v1, v1
	v_add_f32_e32 v5, v0, v10
	ds_write_b64 v95, v[6:7] offset:224
	v_cndmask_b32_e32 v1, 0, v1, vcc
	v_cmp_lt_f32_e32 vcc, s67, v3
	v_sub_f32_e32 v3, v3, v2
	v_mul_f32_e32 v3, 0x3fb8aa3b, v3
	v_exp_f32_e32 v3, v3
	v_add_f32_e32 v5, v1, v5
	v_cvt_pk_bf16_f32 v0, v0, v1
	v_cndmask_b32_e32 v3, 0, v3, vcc
	v_cmp_lt_f32_e32 vcc, s67, v4
	v_sub_f32_e32 v4, v4, v2
	v_mul_f32_e32 v4, 0x3fb8aa3b, v4
	v_exp_f32_e32 v4, v4
	v_add_f32_e32 v5, v3, v5
	v_cndmask_b32_e32 v4, 0, v4, vcc
	v_add_f32_e32 v5, v4, v5
	v_cvt_pk_bf16_f32 v1, v3, v4
	ds_write2_b64 v95, v[0:1], v[12:13] offset0:32 offset1:36
	ds_bpermute_b32 v0, v96, v5
	s_waitcnt lgkmcnt(0)
	s_barrier
; __device__ __forceinline__ unsigned cvt_pk_bf16(float lo, float hi) { unsigned r; asm volatile("v_cvt_pk_bf16_f32 %0, %1, %2" : "=v"(r) : "v"(lo), "v"(hi)); return r; }
; #define LAS __attribute__((address_space(3)))
; __device__ __forceinline__ void attn_prompt_item(LAS unsigned char* lds, const bf16_t* qkvb, bf16_t* og, float* lse, int it, int tid, int wave, int lane) {
;     ...
;     den += __shfl_xor(den, 16); den += __shfl_xor(den, 32);
;     const float inv = 1.0f / den;
;     __syncthreads();
;     bf16_t* op = og + qrow * AW + g * 256 + hh * 64 + 4 * fq;
; #pragma unroll
;     for (int dt = 0; dt < 4; ++dt) {
;         f32x4 o = (f32x4){0.f, 0.f, 0.f, 0.f};
; #pragma unroll
;         for (int ks = 0; ks < 5; ++ks) {
;             const bf16x8 av = *(const LAS bf16x8*)(Vt + (16 * dt + ql) * VT_PITCH + (((2 * wave + 4 * ks + fq) ^ ((2 * dt + (ql >> 3)) & 7)) << 3));
;             const bf16x8 bp = *(const LAS bf16x8*)(Pw + ql * PW_PITCH + 32 * ks + 8 * fq);
;             o = __builtin_amdgcn_mfma_f32_16x16x32_bf16(av, bp, o, 0, 0, 0); }
;         u32x2 w; w.x = cvt_pk_bf16(o[0] * inv, o[1] * inv); w.y = cvt_pk_bf16(o[2] * inv, o[3] * inv);
;         *(u32x2*)(op + 16 * dt) = w;
;     }
;     if (fq == 0) lse[qrow * 12 + g * 4 + hh] = mx + __logf(den);
	v_lshlrev_b32_e32 v12, 1, v150
	v_add_f32_e32 v0, v5, v0
	ds_bpermute_b32 v1, v97, v0
	s_waitcnt lgkmcnt(0)
	v_add_f32_e32 v3, v0, v1
	v_div_scale_f32 v0, s[6:7], v3, v3, 1.0
	v_rcp_f32_e32 v1, v0
	s_nop 0
	v_fma_f32 v4, -v0, v1, 1.0
	v_fmac_f32_e32 v1, v4, v1
	v_div_scale_f32 v4, vcc, 1.0, v3, 1.0
	v_mul_f32_e32 v5, v4, v1
	v_fma_f32 v6, -v0, v5, v4
	v_fmac_f32_e32 v5, v6, v1
	v_fma_f32 v0, -v0, v5, v4
	v_div_fmas_f32 v0, v0, v1, v5
	v_div_fixup_f32 v17, v0, v3, 1.0
	v_mov_b64_e32 v[0:1], s[34:35]
	v_mad_u64_u32 v[0:1], s[6:7], v18, s27, v[0:1]
	v_mov_b32_e32 v4, v1
	v_mad_u64_u32 v[4:5], s[6:7], v19, s27, v[4:5]
	v_mov_b32_e32 v1, v4
	ds_read_b128 v[4:7], v111 offset:36864
	v_lshl_add_u64 v[0:1], v[0:1], 0, s[80:81]
	v_lshl_add_u64 v[0:1], v[0:1], 0, s[28:29]
	v_lshl_add_u64 v[0:1], v[0:1], 0, v[12:13]
	v_add_u32_e32 v12, v95, v154
	ds_read_b128 v[8:11], v12
	s_waitcnt lgkmcnt(0)
	v_mfma_f32_16x16x32_bf16 v[4:7], v[4:7], v[8:11], 0
	ds_read_b128 v[8:11], v112 offset:36864
	ds_read_b128 v[136:139], v12 offset:64
	s_waitcnt lgkmcnt(0)
	v_mfma_f32_16x16x32_bf16 v[4:7], v[8:11], v[136:139], v[4:7]
	ds_read_b128 v[8:11], v113 offset:36864
	ds_read_b128 v[136:139], v12 offset:128
	s_waitcnt lgkmcnt(0)
	v_mfma_f32_16x16x32_bf16 v[4:7], v[8:11], v[136:139], v[4:7]
	ds_read_b128 v[8:11], v114 offset:36864
	ds_read_b128 v[136:139], v12 offset:192
	s_waitcnt lgkmcnt(0)
	v_mfma_f32_16x16x32_bf16 v[4:7], v[8:11], v[136:139], v[4:7]
	ds_read_b128 v[8:11], v115 offset:36864
	ds_read_b128 v[136:139], v12 offset:256
	s_waitcnt lgkmcnt(0)
	v_mfma_f32_16x16x32_bf16 v[4:7], v[8:11], v[136:139], v[4:7]
	s_nop 7
	v_mul_f32_e32 v4, v17, v4
	v_mul_f32_e32 v5, v17, v5
	v_cvt_pk_bf16_f32 v4, v4, v5
	v_mul_f32_e32 v5, v17, v6
	v_mul_f32_e32 v6, v17, v7
	v_cvt_pk_bf16_f32 v5, v5, v6
	global_store_dwordx2 v[0:1], v[4:5], off
	ds_read_b128 v[4:7], v116 offset:47360
	ds_read_b128 v[8:11], v12
	s_waitcnt lgkmcnt(0)
	v_mfma_f32_16x16x32_bf16 v[4:7], v[4:7], v[8:11], 0
	ds_read_b128 v[8:11], v117 offset:47360
	ds_read_b128 v[136:139], v12 offset:64
	s_waitcnt lgkmcnt(0)
	v_mfma_f32_16x16x32_bf16 v[4:7], v[8:11], v[136:139], v[4:7]
	ds_read_b128 v[8:11], v118 offset:47360
	ds_read_b128 v[136:139], v12 offset:128
	s_waitcnt lgkmcnt(0)
	v_mfma_f32_16x16x32_bf16 v[4:7], v[8:11], v[136:139], v[4:7]
	ds_read_b128 v[8:11], v119 offset:47360
	ds_read_b128 v[136:139], v12 offset:192
	s_waitcnt lgkmcnt(0)
	v_mfma_f32_16x16x32_bf16 v[4:7], v[8:11], v[136:139], v[4:7]
	ds_read_b128 v[8:11], v120 offset:47360
	ds_read_b128 v[136:139], v12 offset:256
	s_waitcnt lgkmcnt(0)
	v_mfma_f32_16x16x32_bf16 v[4:7], v[8:11], v[136:139], v[4:7]
	s_nop 7
	v_mul_f32_e32 v4, v17, v4
	v_mul_f32_e32 v5, v17, v5
	v_cvt_pk_bf16_f32 v4, v4, v5
	v_mul_f32_e32 v5, v17, v6
	v_mul_f32_e32 v6, v17, v7
	v_cvt_pk_bf16_f32 v5, v5, v6
	global_store_dwordx2 v[0:1], v[4:5], off offset:32
	ds_read_b128 v[4:7], v121 offset:57856
	ds_read_b128 v[8:11], v12
	s_waitcnt lgkmcnt(0)
	v_mfma_f32_16x16x32_bf16 v[4:7], v[4:7], v[8:11], 0
	ds_read_b128 v[8:11], v122 offset:57856
	ds_read_b128 v[136:139], v12 offset:64
	s_waitcnt lgkmcnt(0)
	v_mfma_f32_16x16x32_bf16 v[4:7], v[8:11], v[136:139], v[4:7]
	ds_read_b128 v[8:11], v123 offset:57856
	ds_read_b128 v[136:139], v12 offset:128
	s_waitcnt lgkmcnt(0)
	v_mfma_f32_16x16x32_bf16 v[4:7], v[8:11], v[136:139], v[4:7]
	ds_read_b128 v[8:11], v124 offset:57856
	ds_read_b128 v[136:139], v12 offset:192
	s_waitcnt lgkmcnt(0)
	v_mfma_f32_16x16x32_bf16 v[4:7], v[8:11], v[136:139], v[4:7]
	ds_read_b128 v[8:11], v125 offset:57856
	ds_read_b128 v[136:139], v12 offset:256
	s_waitcnt lgkmcnt(0)
	v_mfma_f32_16x16x32_bf16 v[4:7], v[8:11], v[136:139], v[4:7]
	s_nop 7
	v_mul_f32_e32 v4, v17, v4
	v_mul_f32_e32 v5, v17, v5
	v_cvt_pk_bf16_f32 v4, v4, v5
	v_mul_f32_e32 v5, v17, v6
	v_mul_f32_e32 v6, v17, v7
	v_cvt_pk_bf16_f32 v5, v5, v6
	global_store_dwordx2 v[0:1], v[4:5], off offset:64
	ds_read_b128 v[4:7], v126 offset:36864
	ds_read_b128 v[8:11], v12
	s_waitcnt lgkmcnt(0)
	v_mfma_f32_16x16x32_bf16 v[4:7], v[4:7], v[8:11], 0
	ds_read_b128 v[8:11], v127 offset:36864
	ds_read_b128 v[136:139], v12 offset:64
	s_waitcnt lgkmcnt(0)
	v_mfma_f32_16x16x32_bf16 v[4:7], v[8:11], v[136:139], v[4:7]
	ds_read_b128 v[8:11], v130 offset:36864
	ds_read_b128 v[136:139], v12 offset:128
	s_waitcnt lgkmcnt(0)
	v_mfma_f32_16x16x32_bf16 v[4:7], v[8:11], v[136:139], v[4:7]
	ds_read_b128 v[8:11], v131 offset:36864
	ds_read_b128 v[136:139], v12 offset:192
	s_waitcnt lgkmcnt(0)
	v_mfma_f32_16x16x32_bf16 v[4:7], v[8:11], v[136:139], v[4:7]
	ds_read_b128 v[8:11], v132 offset:36864
	ds_read_b128 v[136:139], v12 offset:256
	s_waitcnt lgkmcnt(0)
	v_mfma_f32_16x16x32_bf16 v[4:7], v[8:11], v[136:139], v[4:7]
	s_nop 7
	v_mul_f32_e32 v4, v17, v4
	v_mul_f32_e32 v5, v17, v5
	v_cvt_pk_bf16_f32 v4, v4, v5
	v_mul_f32_e32 v5, v17, v6
	v_mul_f32_e32 v6, v17, v7
	v_cvt_pk_bf16_f32 v5, v5, v6
	global_store_dwordx2 v[0:1], v[4:5], off offset:96
	s_and_saveexec_b64 s[80:81], s[72:73]
	s_cbranch_execz .LBB0_632
	s_mov_b32 s4, 0x800000
	v_cmp_gt_f32_e32 vcc, s4, v3
	s_mov_b32 s4, 0x3f317217
	s_ashr_i32 s79, s78, 31
	v_cndmask_b32_e64 v0, 0, 32, vcc
	v_ldexp_f32 v0, v3, v0
	v_log_f32_e32 v0, v0
	v_cndmask_b32_e32 v1, 0, v135, vcc
	s_lshl_b32 s28, s77, 2
	v_mul_f32_e32 v3, 0x3f317217, v0
	v_fma_f32 v3, v0, s4, -v3
	v_fmac_f32_e32 v3, 0x3377d1cf, v0
	s_mov_b32 s4, 0x7f800000
	v_fmac_f32_e32 v3, 0x3f317217, v0
	v_cmp_lt_f32_e64 vcc, |v0|, s4
	s_nop 1
	v_cndmask_b32_e32 v0, v0, v3, vcc
	v_sub_f32_e32 v0, v0, v1
	v_add_f32_e32 v4, v2, v0
	v_mad_u64_u32 v[0:1], s[6:7], v18, 48, s[38:39]
	v_mov_b32_e32 v2, v1
	v_mad_u64_u32 v[2:3], s[6:7], v19, 48, v[2:3]
	v_mov_b32_e32 v1, v2
	v_lshl_add_u64 v[0:1], s[78:79], 2, v[0:1]
	v_lshl_add_u64 v[0:1], v[0:1], 0, s[28:29]
	global_store_dword v[0:1], v4, off
	s_branch .LBB0_632
